# v42: v36 + attention item epilogue: the four gate loads issued together instead of a load-wait-store ladder
# speedup vs baseline: 1.0034x; 1.0034x over previous
.LBB0_598:
	v_add_u32_e32 v2, s53, v101
	v_ashrrev_i32_e32 v3, 31, v2
	v_or_b32_e32 v1, s60, v103
	v_lshlrev_b64 v[2:3], 11, v[2:3]
	v_lshl_add_u64 v[4:5], s[30:31], 0, v[2:3]
	v_lshlrev_b32_e32 v130, 1, v1
	v_lshl_add_u64 v[4:5], v[4:5], 0, v[130:131]
	global_load_dwordx2 v[6:7], v[4:5], off offset:1024
	global_load_dwordx2 v[14:15], v[4:5], off offset:1056
	global_load_dwordx2 v[16:17], v[4:5], off offset:1088
	global_load_dwordx2 v[18:19], v[4:5], off offset:1120
	ds_bpermute_b32 v1, v105, v118
	v_readlane_b32 s60, v254, 32
	v_readlane_b32 s54, v254, 34
	v_readlane_b32 s58, v254, 46
	v_readlane_b32 s56, v254, 48
	s_waitcnt lgkmcnt(0)
	v_add_f32_e32 v1, v118, v1
	ds_bpermute_b32 v8, v119, v1
	v_readlane_b32 s52, v253, 32
	v_readlane_b32 s61, v254, 33
	v_readlane_b32 s55, v254, 35
	v_readlane_b32 s59, v254, 47
	s_waitcnt lgkmcnt(0)
	v_add_f32_e32 v1, v1, v8
	v_add_f32_e32 v1, v107, v1
	v_div_scale_f32 v8, s[0:1], v1, v1, 1.0
	v_rcp_f32_e32 v9, v8
	s_waitcnt vmcnt(3)
	v_div_scale_f32 v10, vcc, 1.0, v1, 1.0
	v_readlane_b32 s0, v253, 55
	v_fma_f32 v11, -v8, v9, 1.0
	v_fmac_f32_e32 v9, v11, v9
	v_mul_f32_e32 v11, v10, v9
	v_fma_f32 v12, -v8, v11, v10
	v_fmac_f32_e32 v11, v12, v9
	v_fma_f32 v8, -v8, v11, v10
	v_div_fmas_f32 v8, v8, v9, v11
	v_div_fixup_f32 v1, v8, v1, 1.0
	v_mul_f32_e32 v8, v54, v1
	v_mul_f32_e32 v9, v55, v1
	v_mul_f32_e32 v10, v56, v1
	v_mul_f32_e32 v11, v57, v1
	v_readlane_b32 s1, v253, 56
	v_readlane_b32 s57, v254, 49
	v_readlane_b32 s53, v253, 33
	v_lshl_add_u64 v[2:3], s[0:1], 0, v[2:3]
	v_lshl_add_u64 v[2:3], v[2:3], 0, v[130:131]
	v_readlane_b32 s79, v254, 50
	s_mov_b32 s64, s44
	s_movk_i32 s73, 0xf0
	s_movk_i32 s62, 0x90
	v_lshlrev_b32_e32 v12, 16, v6
	v_and_b32_e32 v6, 0xffff0000, v6
	v_lshlrev_b32_e32 v13, 16, v7
	v_and_b32_e32 v7, 0xffff0000, v7
	v_mul_f32_e32 v8, v8, v12
	v_mul_f32_e32 v6, v9, v6
	v_mul_f32_e32 v9, v10, v13
	v_mul_f32_e32 v7, v11, v7
	v_cvt_pk_bf16_f32 v6, v8, v6
	v_cvt_pk_bf16_f32 v7, v9, v7
	s_nop 0
	v_mul_f32_e32 v10, v46, v1
	v_mul_f32_e32 v11, v47, v1
	v_mul_f32_e32 v12, v48, v1
	v_mul_f32_e32 v13, v49, v1
	global_store_dwordx2 v[2:3], v[6:7], off offset:1024
	s_waitcnt vmcnt(3)
	v_lshlrev_b32_e32 v6, 16, v14
	v_and_b32_e32 v7, 0xffff0000, v14
	v_lshlrev_b32_e32 v8, 16, v15
	v_and_b32_e32 v9, 0xffff0000, v15
	v_mul_f32_e32 v6, v10, v6
	v_mul_f32_e32 v7, v11, v7
	v_mul_f32_e32 v8, v12, v8
	v_mul_f32_e32 v9, v13, v9
	v_cvt_pk_bf16_f32 v6, v6, v7
	v_cvt_pk_bf16_f32 v7, v8, v9
	s_nop 0
	v_mul_f32_e32 v10, v42, v1
	v_mul_f32_e32 v11, v43, v1
	global_store_dwordx2 v[2:3], v[6:7], off offset:1056
	v_mul_f32_e32 v12, v44, v1
	v_mul_f32_e32 v13, v45, v1
	s_waitcnt vmcnt(3)
	v_lshlrev_b32_e32 v6, 16, v16
	v_and_b32_e32 v7, 0xffff0000, v16
	v_lshlrev_b32_e32 v8, 16, v17
	v_and_b32_e32 v9, 0xffff0000, v17
	v_mul_f32_e32 v6, v10, v6
	v_mul_f32_e32 v7, v11, v7
	v_mul_f32_e32 v8, v12, v8
	v_mul_f32_e32 v9, v13, v9
	v_cvt_pk_bf16_f32 v6, v6, v7
	v_cvt_pk_bf16_f32 v7, v8, v9
	s_nop 0
	v_mul_f32_e32 v9, v51, v1
	global_store_dwordx2 v[2:3], v[6:7], off offset:1088
	v_mul_f32_e32 v8, v50, v1
	v_mul_f32_e32 v10, v52, v1
	v_mul_f32_e32 v1, v53, v1
	s_waitcnt vmcnt(3)
	v_lshlrev_b32_e32 v6, 16, v18
	v_and_b32_e32 v4, 0xffff0000, v18
	v_lshlrev_b32_e32 v7, 16, v19
	v_and_b32_e32 v5, 0xffff0000, v19
	v_mul_f32_e32 v4, v9, v4
	v_mul_f32_e32 v6, v8, v6
	v_mul_f32_e32 v7, v10, v7
	v_mul_f32_e32 v1, v1, v5
	v_cvt_pk_bf16_f32 v4, v6, v4
	v_cvt_pk_bf16_f32 v5, v7, v1
	global_store_dwordx2 v[2:3], v[4:5], off offset:1120
